# pass prologue: first waits cover only the tile-0 loads; Q and tile-1 loads stay in flight across the LDS writes and barriers
# speedup vs baseline: 1.0056x; 1.0056x over previous
.LBB0_336:
	v_mov_b32_e32 v52, v162
	v_mov_b32_e32 v123, v99
	v_ashrrev_i32_e32 v50, 4, v52
	v_lshlrev_b32_e32 v20, 3, v52
	v_add_u32_e32 v21, 32, v50
	v_and_b32_e32 v24, 0x78, v20
	v_mad_i64_i32 v[2:3], s[12:13], v50, s52, 0
	v_mad_i64_i32 v[4:5], s[12:13], v21, s52, 0
	v_or_b32_e32 v2, v2, v24
	v_or_b32_e32 v4, v4, v24
	v_lshlrev_b64 v[10:11], 1, v[2:3]
	v_lshlrev_b64 v[12:13], 1, v[4:5]
	v_lshl_add_u64 v[2:3], s[36:37], 0, v[10:11]
	v_lshl_add_u64 v[6:7], s[36:37], 0, v[12:13]
	v_lshl_add_u64 v[10:11], s[34:35], 0, v[10:11]
	v_lshl_add_u64 v[14:15], s[34:35], 0, v[12:13]
	global_load_dwordx4 v[2:5], v[2:3], off
	s_nop 0
	global_load_dwordx4 v[6:9], v[6:7], off
	s_nop 0
	global_load_dwordx4 v[10:13], v[10:11], off
	s_nop 0
	global_load_dwordx4 v[14:17], v[14:15], off
	s_lshl_b32 s12, s8, 7
	s_add_u32 s8, s76, s12
	s_addc_u32 s9, s77, 0
	v_ashrrev_i32_e32 v26, 1, v52
	v_bfe_u32 v51, v52, 5, 1
	v_bfi_b32 v23, s18, v26, v52
	v_mov_b64_e32 v[18:19], s[8:9]
	v_bfe_u32 v27, v20, 5, 2
	v_lshlrev_b32_e32 v28, 5, v50
	v_and_b32_e32 v20, 24, v20
	v_add_u32_e32 v30, 64, v50
	v_lshrrev_b32_e32 v22, 5, v52
	v_lshlrev_b32_e32 v98, 4, v51
	v_add_u32_e32 v31, 0x60, v50
	v_mad_i64_i32 v[18:19], s[8:9], v23, s49, v[18:19]
	v_and_or_b32 v28, v28, s51, v20
	v_lshrrev_b32_e32 v33, 1, v21
	v_lshlrev_b32_e32 v35, 8, v21
	v_mad_i64_i32 v[20:21], s[8:9], v30, s52, 0
	v_and_or_b32 v32, v22, s50, v27
	v_mad_i64_i32 v[22:23], s[8:9], v31, s52, 0
	v_lshl_add_u64 v[18:19], v[18:19], 0, v[98:99]
	v_lshlrev_b32_e32 v28, 1, v28
	v_or_b32_e32 v20, v20, v24
	v_and_b32_e32 v25, 0x70, v52
	v_lshlrev_b32_e32 v29, 8, v50
	v_lshlrev_b32_e32 v34, 1, v24
	v_and_or_b32 v27, v33, s50, v27
	v_or_b32_e32 v22, v22, v24
	global_load_dwordx4 v[118:121], v[18:19], off
	global_load_dwordx4 v[114:117], v[18:19], off offset:32
	global_load_dwordx4 v[110:113], v[18:19], off offset:64
	global_load_dwordx4 v[106:109], v[18:19], off offset:96
	v_lshl_or_b32 v24, v32, 9, v28
	v_lshlrev_b64 v[18:19], 1, v[20:21]
	v_bitop3_b32 v29, v34, v29, v25 bitop3:0xde
	v_bitop3_b32 v25, v34, v35, v25 bitop3:0xde
	v_lshl_or_b32 v27, v27, 9, v28
	v_lshlrev_b64 v[20:21], 1, v[22:23]
	v_add_u32_e32 v183, 0, v24
	v_lshl_add_u64 v[22:23], s[36:37], 0, v[18:19]
	v_add_u32_e32 v181, 0, v29
	v_add_u32_e32 v182, 0, v25
	v_add_u32_e32 v184, 0, v27
	v_lshl_add_u64 v[24:25], s[36:37], 0, v[20:21]
	v_lshl_add_u64 v[18:19], s[34:35], 0, v[18:19]
	v_lshl_add_u64 v[20:21], s[34:35], 0, v[20:21]
	global_load_dwordx4 v[34:37], v[22:23], off
	global_load_dwordx4 v[38:41], v[24:25], off
	global_load_dwordx4 v[42:45], v[18:19], off
	global_load_dwordx4 v[46:49], v[20:21], off
	s_waitcnt vmcnt(8)
	v_and_b32_e32 v55, 63, v52
	v_and_b32_e32 v54, 0xffffffe0, v26
	v_and_b32_e32 v53, 31, v52
	v_add_u32_e32 v185, s75, v54
	v_cmp_gt_u32_e32 vcc, 32, v55
	v_or_b32_e32 v178, v185, v53
	v_mov_b32_e32 v124, v99
	v_cndmask_b32_e32 v122, 0, v170, vcc
	v_mov_b32_e32 v125, v99
	s_barrier
	s_waitcnt vmcnt(8)
	ds_write_b128 v183, v[2:5]
	s_waitcnt vmcnt(8)
	ds_write_b128 v184, v[6:9]
	s_movk_i32 s101, 0x80
	v_lshrrev_b32_e32 v253, 4, v181
	v_bfi_b32 v181, s101, v253, v181
	v_lshrrev_b32_e32 v253, 4, v182
	v_bfi_b32 v182, s101, v253, v182
	v_and_b32_e32 v253, 8, v52
	s_lshr_b32 s100, s12, 4
	v_cmp_eq_u32_e64 s[96:97], s100, v253
	s_waitcnt vmcnt(8)
	s_mov_b64 s[100:101], exec
	s_and_b64 exec, exec, s[96:97]
	ds_write_b128 v181, v[10:13] offset:32768
	ds_write_b128 v182, v[14:17] offset:32768
	s_mov_b64 exec, s[100:101]
	s_waitcnt lgkmcnt(0)
	s_barrier
	ds_read_b32 v2, v173
	ds_read_b32 v3, v171
	s_waitcnt lgkmcnt(1)
	v_readfirstlane_b32 s43, v2
	s_waitcnt lgkmcnt(0)
	v_readfirstlane_b32 s42, v3
	v_lshlrev_b32_e32 v18, 4, v52
	v_mfma_f32_32x32x16_bf16 v[2:17], v[122:125], v[102:105], 0
	v_lshlrev_b32_e32 v64, 8, v53
	v_and_b32_e32 v65, 0x70, v18
	s_add_i32 s8, s12, 0
	v_bitop3_b32 v18, v98, v64, v65 bitop3:0xde
	v_and_b32_e32 v253, 8, v53
	v_lshlrev_b32_e32 v253, 4, v253
	v_add_u32_e32 v186, v253, v18
	ds_read_b128 v[56:59], v186 offset:32768
	ds_read_b128 v[60:63], v186 offset:40960
	v_lshlrev_b32_e32 v179, 2, v51
	s_waitcnt vmcnt(7) lgkmcnt(1)
	v_mfma_f32_32x32x16_bf16 v[18:33], v[56:59], v[118:121], v[2:17]
	v_or_b32_e32 v56, 32, v98
	v_bitop3_b32 v56, v56, v64, v65 bitop3:0xde
	v_add_u32_e32 v187, v253, v56
	s_waitcnt lgkmcnt(0)
	v_mfma_f32_32x32x16_bf16 v[2:17], v[60:63], v[118:121], v[2:17]
	ds_read_b128 v[56:59], v187 offset:32768
	ds_read_b128 v[60:63], v187 offset:40960
	s_waitcnt vmcnt(6) lgkmcnt(1)
	v_mfma_f32_32x32x16_bf16 v[18:33], v[56:59], v[114:117], v[18:33]
	v_or_b32_e32 v56, 64, v98
	v_bitop3_b32 v56, v56, v64, v65 bitop3:0xde
	v_add_u32_e32 v188, v253, v56
	s_waitcnt lgkmcnt(0)
	v_mfma_f32_32x32x16_bf16 v[2:17], v[60:63], v[114:117], v[2:17]
	ds_read_b128 v[56:59], v188 offset:32768
	ds_read_b128 v[60:63], v188 offset:40960
	s_waitcnt vmcnt(5) lgkmcnt(1)
	v_mfma_f32_32x32x16_bf16 v[18:33], v[56:59], v[110:113], v[18:33]
	v_or_b32_e32 v56, 0x60, v98
	v_bitop3_b32 v56, v56, v64, v65 bitop3:0xde
	v_add_u32_e32 v189, v253, v56
	s_waitcnt lgkmcnt(0)
	v_mfma_f32_32x32x16_bf16 v[2:17], v[60:63], v[110:113], v[2:17]
	ds_read_b128 v[56:59], v189 offset:32768
	ds_read_b128 v[60:63], v189 offset:40960
	s_waitcnt vmcnt(4) lgkmcnt(1)
	v_mfma_f32_32x32x16_bf16 v[18:33], v[56:59], v[106:109], v[18:33]
	v_add_u32_e32 v56, 0x9e, v185
	v_cmp_gt_u32_e64 s[8:9], s53, v56
	s_waitcnt lgkmcnt(0)
	v_mfma_f32_32x32x16_bf16 v[2:17], v[60:63], v[106:109], v[2:17]
	s_and_saveexec_b64 s[12:13], s[8:9]
	s_cbranch_execz .LBB0_338
	v_sub_u32_e32 v51, v179, v178
	v_lshl_add_u32 v51, v51, 2, s1
	ds_read2_b32 v[56:57], v51 offset0:240 offset1:241
	ds_read2_b32 v[58:59], v51 offset0:242 offset1:243
	ds_read2_b32 v[60:61], v51 offset0:248 offset1:249
	ds_read2_b32 v[62:63], v51 offset0:250 offset1:251
	ds_read2_b32 v[64:65], v51 offset0:224 offset1:225
	ds_read2_b32 v[66:67], v51 offset0:226 offset1:227
	ds_read2_b32 v[68:69], v51 offset0:232 offset1:233
	ds_read2_b32 v[70:71], v51 offset0:234 offset1:235
	s_waitcnt lgkmcnt(4)
	v_add_f32_e32 v32, v32, v62
	v_add_f32_e32 v33, v33, v63
	v_add_f32_e32 v30, v30, v60
	v_add_f32_e32 v31, v31, v61
	v_add_f32_e32 v28, v28, v58
	v_add_f32_e32 v29, v29, v59
	v_add_f32_e32 v26, v26, v56
	v_add_f32_e32 v27, v27, v57
	s_waitcnt lgkmcnt(0)
	v_add_f32_e32 v24, v24, v70
	v_add_f32_e32 v25, v25, v71
	v_add_f32_e32 v22, v22, v68
	v_add_f32_e32 v23, v23, v69
	v_add_f32_e32 v20, v20, v66
	v_add_f32_e32 v21, v21, v67
	v_add_f32_e32 v18, v18, v64
	v_add_f32_e32 v19, v19, v65
	v_add_u32_e32 v64, 0x400, v51
	v_add_u32_e32 v66, 0x408, v51
	v_add_u32_e32 v68, 0x420, v51
	v_add_u32_e32 v70, 0x428, v51
	v_add_u32_e32 v56, 0x440, v51
	v_add_u32_e32 v58, 0x448, v51
	v_add_u32_e32 v60, 0x460, v51
	v_add_u32_e32 v51, 0x468, v51
	ds_read2_b32 v[56:57], v56 offset1:1
	ds_read2_b32 v[58:59], v58 offset1:1
	ds_read2_b32 v[60:61], v60 offset1:1
	ds_read2_b32 v[62:63], v51 offset1:1
	ds_read2_b32 v[64:65], v64 offset1:1
	ds_read2_b32 v[66:67], v66 offset1:1
	ds_read2_b32 v[68:69], v68 offset1:1
	ds_read2_b32 v[70:71], v70 offset1:1
	s_waitcnt lgkmcnt(4)
	v_add_f32_e32 v16, v16, v62
	v_add_f32_e32 v17, v17, v63
	v_add_f32_e32 v14, v14, v60
	v_add_f32_e32 v15, v15, v61
	v_add_f32_e32 v12, v12, v58
	v_add_f32_e32 v13, v13, v59
	v_add_f32_e32 v10, v10, v56
	v_add_f32_e32 v11, v11, v57
	s_waitcnt lgkmcnt(0)
	v_add_f32_e32 v8, v8, v70
	v_add_f32_e32 v9, v9, v71
	v_add_f32_e32 v6, v6, v68
	v_add_f32_e32 v7, v7, v69
	v_add_f32_e32 v4, v4, v66
	v_add_f32_e32 v5, v5, v67
	v_add_f32_e32 v2, v2, v64
	v_add_f32_e32 v3, v3, v65
